# GEMM-tail weight conversions moved from the start of in0/in1/out1/in2 phases to their end junction (blocks with one unit less convert after their units)
# baseline (speedup 1.0000x reference)
.LBB0_279:
	s_add_u32 s66, s52, 0x8b00000
	s_addc_u32 s67, s53, 0
	s_add_u32 s82, s52, 0x15700000
	s_addc_u32 s83, s53, 0
	s_add_u32 s48, s52, 0x22300000
	s_addc_u32 s5, s53, 0
	s_add_u32 s44, s52, 0x26700000
	s_addc_u32 s71, s53, 0
	v_writelane_b32 v255, s57, 10
	s_mov_b32 s4, s48
	s_add_u32 s68, s52, 0x2ef00000
	v_writelane_b32 v255, s4, 11
	s_addc_u32 s69, s53, 0
	s_mov_b32 s70, s44
	v_writelane_b32 v255, s5, 12
	s_add_u32 s4, s52, 0x400000
	s_addc_u32 s5, s53, 0
	v_writelane_b32 v255, s4, 13
	s_nop 1
	v_writelane_b32 v255, s5, 14
	s_add_u32 s4, s52, 0x600000
	s_addc_u32 s5, s53, 0
	s_add_u32 s74, s52, 0x700000
	s_addc_u32 s75, s53, 0
	s_add_u32 s62, s52, 0x780000
	s_addc_u32 s63, s53, 0
	s_add_u32 s64, s52, 0x800000
	v_writelane_b32 v255, s4, 15
	s_addc_u32 s65, s53, 0
	s_cmp_lt_i32 s61, 3
	v_writelane_b32 v255, s5, 16
	s_cbranch_scc1 .LBB0_1001
	s_cmp_gt_i32 s60, 2
	s_cbranch_scc1 .LBB0_353
	s_cmpk_lg_i32 s56, 0x100
	s_cselect_b64 s[4:5], -1, 0
	s_cmpk_lt_i32 s2, 0x60
	s_cselect_b64 s[6:7], -1, 0
	s_or_b64 s[4:5], s[6:7], s[4:5]
	s_and_b64 vcc, exec, s[4:5]
	s_cbranch_vccnz .LBB0_285
	s_add_i32 s4, s54, 0x1d00
	s_cmpk_gt_i32 s4, 0
	s_cbranch_scc1 .LBB0_285
	v_readlane_b32 s5, v255, 6
	s_add_u32 s3, s52, 0x2b00000
	s_mulk_i32 s5, 0x2200
	s_addc_u32 s6, s53, 0
	s_add_i32 s8, s5, 0
	v_and_b32_e32 v1, 63, v0
	s_mov_b32 s7, 0x10000
	s_add_i32 s8, s8, 0x10000
	s_add_i32 s9, s54, 0x1800
	s_lshl_b32 s10, s4, 1
	s_lshl_b32 s11, s4, 5
	s_movk_i32 s12, 0xc8
	v_mov_b32_e32 v3, 0
	s_movk_i32 s13, 0x2000
	s_movk_i32 s14, 0x4000
	s_movk_i32 s15, 0x6000
	s_mov_b32 s16, 0x8000
	s_mov_b32 s17, 0xa000
	s_mov_b32 s18, 0xc000
	s_mov_b32 s19, 0xe000
	s_mov_b32 s20, 0x12000
	s_mov_b32 s21, 0x14000
	s_mov_b32 s22, 0x16000
	s_mov_b32 s23, 0x18000
	s_mov_b32 s24, 0x1a000
	s_mov_b32 s25, 0x1c000
	s_mov_b32 s26, 0x1e000
	s_mov_b32 s27, 0x20000
	s_mov_b32 s28, 0x22000
	s_mov_b32 s29, 0x24000
	s_mov_b32 s30, 0x26000
	s_mov_b32 s31, 0x28000
	s_mov_b32 s34, 0x2a000
	s_mov_b32 s35, 0x2c000
	s_mov_b32 s36, 0x2e000
	s_mov_b32 s37, 0x30000
	s_mov_b32 s38, 0x32000
	s_mov_b32 s39, 0x34000
	s_mov_b32 s41, 0x36000
	s_mov_b32 s42, 0x38000
	s_mov_b32 s43, 0x3a000
	s_mov_b32 s45, 0x3c000
	s_mov_b32 s46, 0x3e000
	s_movk_i32 s47, 0x84

.LBB0_303:
	v_writelane_b32 v129, s3, 0
	v_writelane_b32 v129, s4, 1
	v_writelane_b32 v129, s5, 2
	v_writelane_b32 v129, s6, 3
	v_writelane_b32 v129, s7, 4
	v_writelane_b32 v129, s8, 5
	v_writelane_b32 v129, s9, 6
	v_writelane_b32 v129, s10, 7
	v_writelane_b32 v129, s11, 8
	v_writelane_b32 v129, s12, 9
	v_writelane_b32 v129, s13, 10
	v_writelane_b32 v129, s14, 11
	v_writelane_b32 v129, s15, 12
	v_writelane_b32 v129, s16, 13
	v_writelane_b32 v129, s17, 14
	v_writelane_b32 v129, s18, 15
	v_writelane_b32 v129, s19, 16
	v_writelane_b32 v129, s20, 17
	v_writelane_b32 v129, s21, 18
	v_writelane_b32 v129, s22, 19
	v_writelane_b32 v129, s23, 20
	v_writelane_b32 v129, s24, 21
	v_writelane_b32 v129, s25, 22
	v_writelane_b32 v129, s26, 23
	v_writelane_b32 v129, s27, 24
	v_writelane_b32 v129, s28, 25
	v_writelane_b32 v129, s29, 26
	v_writelane_b32 v129, s30, 27
	v_writelane_b32 v129, s31, 28
	v_writelane_b32 v129, s33, 29
	v_writelane_b32 v129, s34, 30
	v_writelane_b32 v129, s35, 31
	v_writelane_b32 v129, s36, 32
	v_writelane_b32 v129, s37, 33
	v_writelane_b32 v129, s38, 34
	v_writelane_b32 v129, s39, 35
	v_writelane_b32 v129, s41, 36
	v_writelane_b32 v129, s42, 37
	v_writelane_b32 v129, s43, 38
	v_writelane_b32 v129, s45, 39
	v_writelane_b32 v129, s46, 40
	v_writelane_b32 v129, s47, 41
	v_writelane_b32 v129, s49, 42
	v_writelane_b32 v129, s57, 43
	v_writelane_b32 v129, s58, 44
	v_writelane_b32 v129, s59, 45
	v_writelane_b32 v129, s72, 46
	v_writelane_b32 v129, s73, 47
	v_writelane_b32 v129, s76, 48
	v_writelane_b32 v129, s77, 49
	v_writelane_b32 v129, s78, 50
	v_writelane_b32 v129, s79, 51
	v_writelane_b32 v129, s80, 52
	v_writelane_b32 v129, s81, 53
	v_writelane_b32 v129, s84, 54
	v_writelane_b32 v129, s85, 55
	v_writelane_b32 v129, s86, 56
	v_writelane_b32 v129, s87, 57
	v_writelane_b32 v129, s88, 58
	v_writelane_b32 v129, s89, 59
	v_writelane_b32 v129, s90, 60
	v_writelane_b32 v129, s91, 61
	v_writelane_b32 v129, s92, 62
	v_writelane_b32 v129, s93, 63
	s_cmpk_lt_u32 s2, 0x60
	s_cselect_b64 s[4:5], -1, 0
	s_cmpk_gt_u32 s2, 0x5f
	s_cselect_b64 s[10:11], -1, 0
	s_mov_b32 s3, 0x2000
	s_and_b64 s[6:7], s[10:11], exec
	s_cselect_b32 s12, s3, 0x4000
	s_mov_b32 s3, 0x4000
	s_cselect_b32 s13, 0x4000, s3
	s_add_i32 s14, s54, 0xc000
	s_cmpk_eq_i32 s56, 0x100
	s_cselect_b64 s[6:7], -1, 0
	s_and_b64 s[8:9], s[6:7], exec
	s_cselect_b32 s18, s13, 0
	s_cselect_b32 s19, s12, s14
	s_mov_b32 s3, 0xc000
	s_cmp_ge_u32 s19, s18
	s_mov_b32 s20, 0x12000
	s_waitcnt vmcnt(0)
	s_barrier
	s_cbranch_scc1 .Lcvl0_end
	v_readlane_b32 s8, v255, 7
	s_sub_i32 s8, s8, 0x300
	v_readlane_b32 s13, v255, 6
	s_add_i32 s21, s13, s8
	s_lshl_b32 s22, s21, 1
	s_movk_i32 s12, 0xa00
	s_and_b64 s[8:9], s[10:11], exec
	s_cselect_b32 s12, s12, 0x400
	s_and_b64 s[8:9], s[6:7], exec
	s_mul_i32 s8, s13, 0x2200
	s_cselect_b32 s23, s12, s55
	s_add_i32 s25, s8, 0
	v_cndmask_b32_e64 v2, 0, 1, s[4:5]
	v_and_b32_e32 v1, 63, v0
	s_mov_b32 s9, 0
	s_mov_b32 s24, 0x10000
	s_add_i32 s25, s25, 0x10000
	s_and_b64 s[10:11], s[10:11], s[6:7]
	v_cmp_ne_u32_e64 s[4:5], 1, v2
	v_mov_b32_e32 v3, 0
	s_movk_i32 s26, 0x2000
	s_movk_i32 s27, 0x4000
	s_movk_i32 s28, 0x6000
	s_mov_b32 s29, 0x8000
	s_mov_b32 s30, 0xa000
	s_mov_b32 s31, 0xe000
	s_mov_b32 s34, 0x14000
	s_mov_b32 s35, 0x16000
	s_mov_b32 s36, 0x18000
	s_mov_b32 s37, 0x1a000
	s_mov_b32 s38, 0x1c000
	s_mov_b32 s39, 0x1e000
	s_mov_b32 s41, 0x20000
	s_mov_b32 s42, 0x22000
	s_mov_b32 s43, 0x24000
	s_mov_b32 s45, 0x26000
	s_mov_b32 s46, 0x28000
	s_mov_b32 s47, 0x2a000
	s_mov_b32 s49, 0x2c000
	s_mov_b32 s57, 0x2e000
	s_mov_b32 s58, 0x30000
	s_mov_b32 s59, 0x32000
	s_mov_b32 s72, 0x34000
	s_mov_b32 s73, 0x36000
	s_mov_b32 s78, 0x38000
	s_mov_b32 s79, 0x3a000
	s_mov_b32 s84, 0x3c000
	s_mov_b32 s85, 0x3e000
	s_movk_i32 s86, 0x84
	s_branch .Lcvl0_2352

.Lcvl0_end:
	s_waitcnt vmcnt(0) lgkmcnt(0)
	s_barrier
	v_readlane_b32 s3, v129, 0
	v_readlane_b32 s4, v129, 1
	v_readlane_b32 s5, v129, 2
	v_readlane_b32 s6, v129, 3
	v_readlane_b32 s7, v129, 4
	v_readlane_b32 s8, v129, 5
	v_readlane_b32 s9, v129, 6
	v_readlane_b32 s10, v129, 7
	v_readlane_b32 s11, v129, 8
	v_readlane_b32 s12, v129, 9
	v_readlane_b32 s13, v129, 10
	v_readlane_b32 s14, v129, 11
	v_readlane_b32 s15, v129, 12
	v_readlane_b32 s16, v129, 13
	v_readlane_b32 s17, v129, 14
	v_readlane_b32 s18, v129, 15
	v_readlane_b32 s19, v129, 16
	v_readlane_b32 s20, v129, 17
	v_readlane_b32 s21, v129, 18
	v_readlane_b32 s22, v129, 19
	v_readlane_b32 s23, v129, 20
	v_readlane_b32 s24, v129, 21
	v_readlane_b32 s25, v129, 22
	v_readlane_b32 s26, v129, 23
	v_readlane_b32 s27, v129, 24
	v_readlane_b32 s28, v129, 25
	v_readlane_b32 s29, v129, 26
	v_readlane_b32 s30, v129, 27
	v_readlane_b32 s31, v129, 28
	v_readlane_b32 s33, v129, 29
	v_readlane_b32 s34, v129, 30
	v_readlane_b32 s35, v129, 31
	v_readlane_b32 s36, v129, 32
	v_readlane_b32 s37, v129, 33
	v_readlane_b32 s38, v129, 34
	v_readlane_b32 s39, v129, 35
	v_readlane_b32 s41, v129, 36
	v_readlane_b32 s42, v129, 37
	v_readlane_b32 s43, v129, 38
	v_readlane_b32 s45, v129, 39
	v_readlane_b32 s46, v129, 40
	v_readlane_b32 s47, v129, 41
	v_readlane_b32 s49, v129, 42
	v_readlane_b32 s57, v129, 43
	v_readlane_b32 s58, v129, 44
	v_readlane_b32 s59, v129, 45
	v_readlane_b32 s72, v129, 46
	v_readlane_b32 s73, v129, 47
	v_readlane_b32 s76, v129, 48
	v_readlane_b32 s77, v129, 49
	v_readlane_b32 s78, v129, 50
	v_readlane_b32 s79, v129, 51
	v_readlane_b32 s80, v129, 52
	v_readlane_b32 s81, v129, 53
	v_readlane_b32 s84, v129, 54
	v_readlane_b32 s85, v129, 55
	v_readlane_b32 s86, v129, 56
	v_readlane_b32 s87, v129, 57
	v_readlane_b32 s88, v129, 58
	v_readlane_b32 s89, v129, 59
	v_readlane_b32 s90, v129, 60
	v_readlane_b32 s91, v129, 61
	v_readlane_b32 s92, v129, 62
	v_readlane_b32 s93, v129, 63
	s_cmp_eq_u32 s61, 3
	s_cbranch_scc1 .LBB0_353
	s_waitcnt vmcnt(0)
	v_cmp_eq_u32_e32 vcc, 0, v0
	s_waitcnt vmcnt(0)
	s_barrier
	s_and_saveexec_b64 s[4:5], vcc
	s_cbranch_execz .LBB0_352
	v_readlane_b32 s3, v255, 10
	s_waitcnt vmcnt(0) expcnt(0) lgkmcnt(0)
	s_nop 0
	v_mov_b32_e32 v1, s3
	ds_read_b32 v3, v1
	ds_read_b32 v1, v1 offset:4
	s_waitcnt lgkmcnt(1)
	v_cmp_ne_u32_e32 vcc, 0, v3
	s_cbranch_vccnz .LBB0_320
	v_readlane_b32 s6, v255, 0
	v_readlane_b32 s7, v255, 1
	s_load_dwordx2 s[10:11], s[6:7], 0x4
	s_add_u32 s6, s52, 0x4200
	s_addc_u32 s7, s53, 0
	s_add_u32 s8, s52, 0x4400
	s_addc_u32 s9, s53, 0
	s_waitcnt lgkmcnt(0)
	s_mul_i32 s3, s10, s56
	s_add_u32 s10, s52, 0x4500
	s_mul_i32 s3, s3, s11
	s_addc_u32 s11, s53, 0
	s_add_u32 s12, s52, 0x4600
	s_addc_u32 s13, s53, 0
	s_add_u32 s14, s52, 0x4700
	s_addc_u32 s15, s53, 0
	s_add_u32 s16, s52, 0x4800
	s_addc_u32 s17, s53, 0
	s_add_u32 s18, s52, 0x4900
	s_addc_u32 s19, s53, 0
	s_add_u32 s20, s52, 0x4a00
	s_addc_u32 s21, s53, 0
	s_add_u32 s22, s52, 0x4b00
	s_addc_u32 s23, s53, 0
	s_add_u32 s24, s52, 0x4c00
	s_addc_u32 s25, s53, 0
	s_add_u32 s26, s52, 0x4d00
	s_addc_u32 s27, s53, 0
	s_add_u32 s28, s52, 0x4e00
	s_addc_u32 s29, s53, 0
	s_add_u32 s30, s52, 0x4f00
	s_addc_u32 s31, s53, 0
	s_add_u32 s34, s52, 0x5000
	s_addc_u32 s35, s53, 0
	s_add_u32 s36, s52, 0x5100
	s_addc_u32 s37, s53, 0
	s_add_u32 s38, s52, 0x5200
	s_addc_u32 s39, s53, 0
	s_add_u32 s42, s52, 0x5300
	s_addc_u32 s43, s53, 0
	s_mov_b32 s41, 1
	v_mov_b32_e32 v17, 0
	s_branch .LBB0_308

.LBB0_1002:
	s_cmp_gt_i32 s60, 14
	s_cbranch_scc1 .LBB0_1075
	s_cmpk_lg_i32 s56, 0x100
	s_cselect_b64 s[4:5], -1, 0
	s_cmpk_lt_i32 s2, 0x60
	s_cselect_b64 s[6:7], -1, 0
	s_or_b64 s[4:5], s[6:7], s[4:5]
	s_and_b64 vcc, exec, s[4:5]
	s_cbranch_vccnz .LBB0_1011
	s_add_i32 s3, s54, 0x6900
	s_cmp_gt_i32 s3, 0
	s_cbranch_scc1 .LBB0_1011
	v_readlane_b32 s4, v255, 6
	s_mulk_i32 s4, 0x2200
	s_add_i32 s11, s4, 0
	v_and_b32_e32 v1, 63, v0
	s_mov_b32 s5, 0
	s_mov_b32 s10, 0x10000
	s_add_i32 s11, s11, 0x10000
	s_lshl_b32 s12, s3, 1
	s_lshl_b32 s13, s3, 5
	s_mov_b32 s14, 0x7b00000
	s_waitcnt vmcnt(0)
	v_mov_b32_e32 v3, 0
	s_movk_i32 s15, 0x2000
	s_movk_i32 s16, 0x4000
	s_movk_i32 s17, 0x6000
	s_mov_b32 s18, 0x8000
	s_mov_b32 s19, 0xa000
	s_mov_b32 s20, 0xc000
	s_mov_b32 s21, 0xe000
	s_mov_b32 s22, 0x12000
	s_mov_b32 s23, 0x14000
	s_mov_b32 s24, 0x16000
	s_mov_b32 s25, 0x18000
	s_mov_b32 s26, 0x1a000
	s_mov_b32 s27, 0x1c000
	s_mov_b32 s28, 0x1e000
	s_mov_b32 s29, 0x20000
	s_mov_b32 s30, 0x22000
	s_mov_b32 s31, 0x24000
	s_mov_b32 s34, 0x26000
	s_mov_b32 s35, 0x28000
	s_mov_b32 s36, 0x2a000
	s_mov_b32 s37, 0x2c000
	s_mov_b32 s38, 0x2e000
	s_mov_b32 s39, 0x30000
	s_mov_b32 s41, 0x32000
	s_mov_b32 s42, 0x34000
	s_mov_b32 s43, 0x36000
	s_mov_b32 s45, 0x38000
	s_mov_b32 s46, 0x3a000
	s_mov_b32 s47, 0x3c000
	s_mov_b32 s49, 0x3e000
	s_movk_i32 s50, 0x84
	s_mov_b32 s51, 0x4b00000
	s_movk_i32 s57, 0xc8
	s_branch .LBB0_1007

.LBB0_1025:
	v_writelane_b32 v129, s3, 0
	v_writelane_b32 v129, s4, 1
	v_writelane_b32 v129, s5, 2
	v_writelane_b32 v129, s6, 3
	v_writelane_b32 v129, s7, 4
	v_writelane_b32 v129, s8, 5
	v_writelane_b32 v129, s9, 6
	v_writelane_b32 v129, s10, 7
	v_writelane_b32 v129, s11, 8
	v_writelane_b32 v129, s12, 9
	v_writelane_b32 v129, s13, 10
	v_writelane_b32 v129, s14, 11
	v_writelane_b32 v129, s15, 12
	v_writelane_b32 v129, s16, 13
	v_writelane_b32 v129, s17, 14
	v_writelane_b32 v129, s18, 15
	v_writelane_b32 v129, s19, 16
	v_writelane_b32 v129, s20, 17
	v_writelane_b32 v129, s21, 18
	v_writelane_b32 v129, s22, 19
	v_writelane_b32 v129, s23, 20
	v_writelane_b32 v129, s24, 21
	v_writelane_b32 v129, s25, 22
	v_writelane_b32 v129, s26, 23
	v_writelane_b32 v129, s27, 24
	v_writelane_b32 v129, s28, 25
	v_writelane_b32 v129, s29, 26
	v_writelane_b32 v129, s30, 27
	v_writelane_b32 v129, s31, 28
	v_writelane_b32 v129, s33, 29
	v_writelane_b32 v129, s34, 30
	v_writelane_b32 v129, s35, 31
	v_writelane_b32 v129, s36, 32
	v_writelane_b32 v129, s37, 33
	v_writelane_b32 v129, s38, 34
	v_writelane_b32 v129, s39, 35
	v_writelane_b32 v129, s41, 36
	v_writelane_b32 v129, s42, 37
	v_writelane_b32 v129, s43, 38
	v_writelane_b32 v129, s45, 39
	v_writelane_b32 v129, s46, 40
	v_writelane_b32 v129, s47, 41
	v_writelane_b32 v129, s49, 42
	v_writelane_b32 v129, s57, 43
	v_writelane_b32 v129, s58, 44
	v_writelane_b32 v129, s59, 45
	v_writelane_b32 v129, s72, 46
	v_writelane_b32 v129, s73, 47
	v_writelane_b32 v129, s76, 48
	v_writelane_b32 v129, s77, 49
	v_writelane_b32 v129, s78, 50
	v_writelane_b32 v129, s79, 51
	v_writelane_b32 v129, s80, 52
	v_writelane_b32 v129, s81, 53
	v_writelane_b32 v129, s84, 54
	v_writelane_b32 v129, s85, 55
	v_writelane_b32 v129, s86, 56
	v_writelane_b32 v129, s87, 57
	v_writelane_b32 v129, s88, 58
	v_writelane_b32 v129, s89, 59
	v_writelane_b32 v129, s90, 60
	v_writelane_b32 v129, s91, 61
	v_writelane_b32 v129, s92, 62
	v_writelane_b32 v129, s93, 63
	s_cmpk_lt_u32 s2, 0x60
	s_cselect_b64 s[4:5], -1, 0
	s_cmpk_gt_u32 s2, 0x5f
	s_cselect_b64 s[10:11], -1, 0
	s_mov_b32 s3, 0x6c00
	s_and_b64 s[6:7], s[10:11], exec
	s_cselect_b32 s12, s3, 0x9400
	s_mov_b32 s3, 0x9400
	s_cselect_b32 s13, 0x9400, s3
	s_add_i32 s14, s54, 0xc000
	s_cmpk_eq_i32 s56, 0x100
	s_cselect_b64 s[6:7], -1, 0
	s_and_b64 s[8:9], s[6:7], exec
	s_cselect_b32 s18, s13, 0
	s_cselect_b32 s19, s12, s14
	s_mov_b32 s3, 0xc000
	s_cmp_ge_u32 s19, s18
	s_mov_b32 s20, 0x12000
	s_waitcnt vmcnt(0)
	s_barrier
	s_cbranch_scc1 .Lcvl1_end
	v_readlane_b32 s8, v255, 7
	s_sub_i32 s8, s8, 0x300
	v_readlane_b32 s13, v255, 6
	s_add_i32 s21, s13, s8
	s_lshl_b32 s22, s21, 1
	s_movk_i32 s12, 0xa00
	s_and_b64 s[8:9], s[10:11], exec
	s_cselect_b32 s12, s12, 0x400
	s_and_b64 s[8:9], s[6:7], exec
	s_mul_i32 s8, s13, 0x2200
	s_cselect_b32 s23, s12, s55
	s_add_i32 s25, s8, 0
	v_cndmask_b32_e64 v2, 0, 1, s[4:5]
	v_and_b32_e32 v1, 63, v0
	s_mov_b32 s9, 0
	s_mov_b32 s24, 0x10000
	s_add_i32 s25, s25, 0x10000
	s_and_b64 s[10:11], s[10:11], s[6:7]
	v_cmp_ne_u32_e64 s[4:5], 1, v2
	v_mov_b32_e32 v3, 0
	s_movk_i32 s26, 0x2000
	s_movk_i32 s27, 0x4000
	s_movk_i32 s28, 0x6000
	s_mov_b32 s29, 0x8000
	s_mov_b32 s30, 0xa000
	s_mov_b32 s31, 0xe000
	s_mov_b32 s34, 0x14000
	s_mov_b32 s35, 0x16000
	s_mov_b32 s36, 0x18000
	s_mov_b32 s37, 0x1a000
	s_mov_b32 s38, 0x1c000
	s_mov_b32 s39, 0x1e000
	s_mov_b32 s41, 0x20000
	s_mov_b32 s42, 0x22000
	s_mov_b32 s43, 0x24000
	s_mov_b32 s45, 0x26000
	s_mov_b32 s46, 0x28000
	s_mov_b32 s47, 0x2a000
	s_mov_b32 s49, 0x2c000
	s_mov_b32 s57, 0x2e000
	s_mov_b32 s58, 0x30000
	s_mov_b32 s59, 0x32000
	s_mov_b32 s72, 0x34000
	s_mov_b32 s73, 0x36000
	s_mov_b32 s78, 0x38000
	s_mov_b32 s79, 0x3a000
	s_mov_b32 s84, 0x3c000
	s_mov_b32 s85, 0x3e000
	s_movk_i32 s86, 0x84
	s_branch .Lcvl1_2352

.Lcvl1_end:
	s_waitcnt vmcnt(0) lgkmcnt(0)
	s_barrier
	v_readlane_b32 s3, v129, 0
	v_readlane_b32 s4, v129, 1
	v_readlane_b32 s5, v129, 2
	v_readlane_b32 s6, v129, 3
	v_readlane_b32 s7, v129, 4
	v_readlane_b32 s8, v129, 5
	v_readlane_b32 s9, v129, 6
	v_readlane_b32 s10, v129, 7
	v_readlane_b32 s11, v129, 8
	v_readlane_b32 s12, v129, 9
	v_readlane_b32 s13, v129, 10
	v_readlane_b32 s14, v129, 11
	v_readlane_b32 s15, v129, 12
	v_readlane_b32 s16, v129, 13
	v_readlane_b32 s17, v129, 14
	v_readlane_b32 s18, v129, 15
	v_readlane_b32 s19, v129, 16
	v_readlane_b32 s20, v129, 17
	v_readlane_b32 s21, v129, 18
	v_readlane_b32 s22, v129, 19
	v_readlane_b32 s23, v129, 20
	v_readlane_b32 s24, v129, 21
	v_readlane_b32 s25, v129, 22
	v_readlane_b32 s26, v129, 23
	v_readlane_b32 s27, v129, 24
	v_readlane_b32 s28, v129, 25
	v_readlane_b32 s29, v129, 26
	v_readlane_b32 s30, v129, 27
	v_readlane_b32 s31, v129, 28
	v_readlane_b32 s33, v129, 29
	v_readlane_b32 s34, v129, 30
	v_readlane_b32 s35, v129, 31
	v_readlane_b32 s36, v129, 32
	v_readlane_b32 s37, v129, 33
	v_readlane_b32 s38, v129, 34
	v_readlane_b32 s39, v129, 35
	v_readlane_b32 s41, v129, 36
	v_readlane_b32 s42, v129, 37
	v_readlane_b32 s43, v129, 38
	v_readlane_b32 s45, v129, 39
	v_readlane_b32 s46, v129, 40
	v_readlane_b32 s47, v129, 41
	v_readlane_b32 s49, v129, 42
	v_readlane_b32 s57, v129, 43
	v_readlane_b32 s58, v129, 44
	v_readlane_b32 s59, v129, 45
	v_readlane_b32 s72, v129, 46
	v_readlane_b32 s73, v129, 47
	v_readlane_b32 s76, v129, 48
	v_readlane_b32 s77, v129, 49
	v_readlane_b32 s78, v129, 50
	v_readlane_b32 s79, v129, 51
	v_readlane_b32 s80, v129, 52
	v_readlane_b32 s81, v129, 53
	v_readlane_b32 s84, v129, 54
	v_readlane_b32 s85, v129, 55
	v_readlane_b32 s86, v129, 56
	v_readlane_b32 s87, v129, 57
	v_readlane_b32 s88, v129, 58
	v_readlane_b32 s89, v129, 59
	v_readlane_b32 s90, v129, 60
	v_readlane_b32 s91, v129, 61
	v_readlane_b32 s92, v129, 62
	v_readlane_b32 s93, v129, 63
	s_cmp_eq_u32 s61, 15
	s_cbranch_scc1 .LBB0_1075
	s_waitcnt vmcnt(0)
	v_cmp_eq_u32_e32 vcc, 0, v0
	s_waitcnt vmcnt(16)
	s_barrier
	s_and_saveexec_b64 s[4:5], vcc
	s_cbranch_execz .LBB0_1074
	v_readlane_b32 s3, v255, 10
	s_waitcnt vmcnt(0) expcnt(0) lgkmcnt(0)
	s_nop 0
	v_mov_b32_e32 v1, s3
	ds_read_b32 v3, v1
	ds_read_b32 v1, v1 offset:4
	s_waitcnt lgkmcnt(1)
	v_cmp_ne_u32_e32 vcc, 0, v3
	s_cbranch_vccnz .LBB0_1042
	v_readlane_b32 s6, v255, 0
	v_readlane_b32 s7, v255, 1
	s_load_dwordx2 s[10:11], s[6:7], 0x4
	s_add_u32 s6, s52, 0x4200
	s_addc_u32 s7, s53, 0
	s_add_u32 s8, s52, 0x4400
	s_addc_u32 s9, s53, 0
	s_waitcnt lgkmcnt(0)
	s_mul_i32 s3, s10, s56
	s_add_u32 s10, s52, 0x4500
	s_mul_i32 s3, s3, s11
	s_addc_u32 s11, s53, 0
	s_add_u32 s12, s52, 0x4600
	s_addc_u32 s13, s53, 0
	s_add_u32 s14, s52, 0x4700
	s_addc_u32 s15, s53, 0
	s_add_u32 s16, s52, 0x4800
	s_addc_u32 s17, s53, 0
	s_add_u32 s18, s52, 0x4900
	s_addc_u32 s19, s53, 0
	s_add_u32 s20, s52, 0x4a00
	s_addc_u32 s21, s53, 0
	s_add_u32 s22, s52, 0x4b00
	s_addc_u32 s23, s53, 0
	s_add_u32 s24, s52, 0x4c00
	s_addc_u32 s25, s53, 0
	s_add_u32 s26, s52, 0x4d00
	s_addc_u32 s27, s53, 0
	s_add_u32 s28, s52, 0x4e00
	s_addc_u32 s29, s53, 0
	s_add_u32 s30, s52, 0x4f00
	s_addc_u32 s31, s53, 0
	s_add_u32 s34, s52, 0x5000
	s_addc_u32 s35, s53, 0
	s_add_u32 s36, s52, 0x5100
	s_addc_u32 s37, s53, 0
	s_add_u32 s38, s52, 0x5200
	s_addc_u32 s39, s53, 0
	s_add_u32 s42, s52, 0x5300
	s_addc_u32 s43, s53, 0
	s_mov_b32 s41, 1
	v_mov_b32_e32 v17, 0
	s_branch .LBB0_1030

.LBB0_1314:
	s_cmp_gt_i32 s60, 18
	s_cselect_b64 s[4:5], -1, 0
	s_cmp_lt_i32 s61, 19
	s_cselect_b64 s[6:7], -1, 0
	s_or_b64 s[4:5], s[4:5], s[6:7]
	s_and_b64 vcc, exec, s[4:5]
	s_cbranch_vccnz .LBB0_1390
	s_cmpk_lg_i32 s56, 0x100
	s_cselect_b64 s[4:5], -1, 0
	s_cmp_lt_i32 s2, 32
	s_cselect_b64 s[6:7], -1, 0
	s_or_b64 s[4:5], s[6:7], s[4:5]
	s_and_b64 vcc, exec, s[4:5]
	s_cbranch_vccnz .LBB0_1323
	s_add_i32 s3, s54, 0x9300
	s_cmp_gt_i32 s3, 0
	s_cbranch_scc1 .LBB0_1323
	v_readlane_b32 s4, v255, 6
	s_mulk_i32 s4, 0x2200
	s_add_i32 s11, s4, 0
	v_and_b32_e32 v1, 63, v0
	s_mov_b32 s5, 0
	s_mov_b32 s10, 0x10000
	s_add_i32 s11, s11, 0x10000
	s_lshl_b32 s12, s3, 1
	s_lshl_b32 s13, s3, 5
	s_mov_b32 s14, 0x7b00000
	s_waitcnt vmcnt(0)
	v_mov_b32_e32 v3, 0
	s_movk_i32 s15, 0x2000
	s_movk_i32 s16, 0x4000
	s_movk_i32 s17, 0x6000
	s_mov_b32 s18, 0x8000
	s_mov_b32 s19, 0xa000
	s_mov_b32 s20, 0xc000
	s_mov_b32 s21, 0xe000
	s_mov_b32 s22, 0x12000
	s_mov_b32 s23, 0x14000
	s_mov_b32 s24, 0x16000
	s_mov_b32 s25, 0x18000
	s_mov_b32 s26, 0x1a000
	s_mov_b32 s27, 0x1c000
	s_mov_b32 s28, 0x1e000
	s_mov_b32 s29, 0x20000
	s_mov_b32 s30, 0x22000
	s_mov_b32 s31, 0x24000
	s_mov_b32 s34, 0x26000
	s_mov_b32 s35, 0x28000
	s_mov_b32 s36, 0x2a000
	s_mov_b32 s37, 0x2c000
	s_mov_b32 s38, 0x2e000
	s_mov_b32 s39, 0x30000
	s_mov_b32 s41, 0x32000
	s_mov_b32 s42, 0x34000
	s_mov_b32 s43, 0x36000
	s_mov_b32 s45, 0x38000
	s_mov_b32 s46, 0x3a000
	s_mov_b32 s47, 0x3c000
	s_mov_b32 s49, 0x3e000
	s_movk_i32 s50, 0x84
	s_mov_b32 s51, 0x4b00000
	s_movk_i32 s57, 0xc8
	s_branch .LBB0_1319

.LBB0_1340:
	v_writelane_b32 v129, s3, 0
	v_writelane_b32 v129, s4, 1
	v_writelane_b32 v129, s5, 2
	v_writelane_b32 v129, s6, 3
	v_writelane_b32 v129, s7, 4
	v_writelane_b32 v129, s8, 5
	v_writelane_b32 v129, s9, 6
	v_writelane_b32 v129, s10, 7
	v_writelane_b32 v129, s11, 8
	v_writelane_b32 v129, s12, 9
	v_writelane_b32 v129, s13, 10
	v_writelane_b32 v129, s14, 11
	v_writelane_b32 v129, s15, 12
	v_writelane_b32 v129, s16, 13
	v_writelane_b32 v129, s17, 14
	v_writelane_b32 v129, s18, 15
	v_writelane_b32 v129, s19, 16
	v_writelane_b32 v129, s20, 17
	v_writelane_b32 v129, s21, 18
	v_writelane_b32 v129, s22, 19
	v_writelane_b32 v129, s23, 20
	v_writelane_b32 v129, s24, 21
	v_writelane_b32 v129, s25, 22
	v_writelane_b32 v129, s26, 23
	v_writelane_b32 v129, s27, 24
	v_writelane_b32 v129, s28, 25
	v_writelane_b32 v129, s29, 26
	v_writelane_b32 v129, s30, 27
	v_writelane_b32 v129, s31, 28
	v_writelane_b32 v129, s33, 29
	v_writelane_b32 v129, s34, 30
	v_writelane_b32 v129, s35, 31
	v_writelane_b32 v129, s36, 32
	v_writelane_b32 v129, s37, 33
	v_writelane_b32 v129, s38, 34
	v_writelane_b32 v129, s39, 35
	v_writelane_b32 v129, s41, 36
	v_writelane_b32 v129, s42, 37
	v_writelane_b32 v129, s43, 38
	v_writelane_b32 v129, s45, 39
	v_writelane_b32 v129, s46, 40
	v_writelane_b32 v129, s47, 41
	v_writelane_b32 v129, s49, 42
	v_writelane_b32 v129, s57, 43
	v_writelane_b32 v129, s58, 44
	v_writelane_b32 v129, s59, 45
	v_writelane_b32 v129, s72, 46
	v_writelane_b32 v129, s73, 47
	v_writelane_b32 v129, s76, 48
	v_writelane_b32 v129, s77, 49
	v_writelane_b32 v129, s78, 50
	v_writelane_b32 v129, s79, 51
	v_writelane_b32 v129, s80, 52
	v_writelane_b32 v129, s81, 53
	v_writelane_b32 v129, s84, 54
	v_writelane_b32 v129, s85, 55
	v_writelane_b32 v129, s86, 56
	v_writelane_b32 v129, s87, 57
	v_writelane_b32 v129, s88, 58
	v_writelane_b32 v129, s89, 59
	v_writelane_b32 v129, s90, 60
	v_writelane_b32 v129, s91, 61
	v_writelane_b32 v129, s92, 62
	v_writelane_b32 v129, s93, 63
	s_cmpk_lt_u32 s2, 0x20
	s_cselect_b64 s[4:5], -1, 0
	s_cmpk_gt_u32 s2, 0x1f
	s_cselect_b64 s[10:11], -1, 0
	s_mov_b32 s3, 0x9400
	s_and_b64 s[6:7], s[10:11], exec
	s_cselect_b32 s12, s3, 0xc000
	s_mov_b32 s3, 0xc000
	s_cselect_b32 s13, 0xc000, s3
	s_add_i32 s14, s54, 0xc000
	s_cmpk_eq_i32 s56, 0x100
	s_cselect_b64 s[6:7], -1, 0
	s_and_b64 s[8:9], s[6:7], exec
	s_cselect_b32 s18, s13, 0
	s_cselect_b32 s19, s12, s14
	s_mov_b32 s3, 0xc000
	s_cmp_ge_u32 s19, s18
	s_mov_b32 s20, 0x12000
	s_waitcnt vmcnt(0)
	s_barrier
	s_cbranch_scc1 .Lcvl2_end
	v_readlane_b32 s8, v255, 7
	s_sub_i32 s8, s8, 0x100
	v_readlane_b32 s13, v255, 6
	s_add_i32 s21, s13, s8
	s_lshl_b32 s22, s21, 1
	s_movk_i32 s12, 0xe00
	s_and_b64 s[8:9], s[10:11], exec
	s_cselect_b32 s12, s12, 0x400
	s_and_b64 s[8:9], s[6:7], exec
	s_mul_i32 s8, s13, 0x2200
	s_cselect_b32 s23, s12, s55
	s_add_i32 s25, s8, 0
	v_cndmask_b32_e64 v2, 0, 1, s[4:5]
	v_and_b32_e32 v1, 63, v0
	s_mov_b32 s9, 0
	s_mov_b32 s24, 0x10000
	s_add_i32 s25, s25, 0x10000
	s_and_b64 s[10:11], s[10:11], s[6:7]
	v_cmp_ne_u32_e64 s[4:5], 1, v2
	v_mov_b32_e32 v3, 0
	s_movk_i32 s26, 0x2000
	s_movk_i32 s27, 0x4000
	s_movk_i32 s28, 0x6000
	s_mov_b32 s29, 0x8000
	s_mov_b32 s30, 0xa000
	s_mov_b32 s31, 0xe000
	s_mov_b32 s34, 0x14000
	s_mov_b32 s35, 0x16000
	s_mov_b32 s36, 0x18000
	s_mov_b32 s37, 0x1a000
	s_mov_b32 s38, 0x1c000
	s_mov_b32 s39, 0x1e000
	s_mov_b32 s41, 0x20000
	s_mov_b32 s42, 0x22000
	s_mov_b32 s43, 0x24000
	s_mov_b32 s45, 0x26000
	s_mov_b32 s46, 0x28000
	s_mov_b32 s47, 0x2a000
	s_mov_b32 s49, 0x2c000
	s_mov_b32 s57, 0x2e000
	s_mov_b32 s58, 0x30000
	s_mov_b32 s59, 0x32000
	s_mov_b32 s72, 0x34000
	s_mov_b32 s73, 0x36000
	s_mov_b32 s78, 0x38000
	s_mov_b32 s79, 0x3a000
	s_mov_b32 s84, 0x3c000
	s_mov_b32 s85, 0x3e000
	s_movk_i32 s86, 0x84
	s_branch .Lcvl2_2352

.Lcvl2_end:
	s_waitcnt vmcnt(0) lgkmcnt(0)
	s_barrier
	v_readlane_b32 s3, v129, 0
	v_readlane_b32 s4, v129, 1
	v_readlane_b32 s5, v129, 2
	v_readlane_b32 s6, v129, 3
	v_readlane_b32 s7, v129, 4
	v_readlane_b32 s8, v129, 5
	v_readlane_b32 s9, v129, 6
	v_readlane_b32 s10, v129, 7
	v_readlane_b32 s11, v129, 8
	v_readlane_b32 s12, v129, 9
	v_readlane_b32 s13, v129, 10
	v_readlane_b32 s14, v129, 11
	v_readlane_b32 s15, v129, 12
	v_readlane_b32 s16, v129, 13
	v_readlane_b32 s17, v129, 14
	v_readlane_b32 s18, v129, 15
	v_readlane_b32 s19, v129, 16
	v_readlane_b32 s20, v129, 17
	v_readlane_b32 s21, v129, 18
	v_readlane_b32 s22, v129, 19
	v_readlane_b32 s23, v129, 20
	v_readlane_b32 s24, v129, 21
	v_readlane_b32 s25, v129, 22
	v_readlane_b32 s26, v129, 23
	v_readlane_b32 s27, v129, 24
	v_readlane_b32 s28, v129, 25
	v_readlane_b32 s29, v129, 26
	v_readlane_b32 s30, v129, 27
	v_readlane_b32 s31, v129, 28
	v_readlane_b32 s33, v129, 29
	v_readlane_b32 s34, v129, 30
	v_readlane_b32 s35, v129, 31
	v_readlane_b32 s36, v129, 32
	v_readlane_b32 s37, v129, 33
	v_readlane_b32 s38, v129, 34
	v_readlane_b32 s39, v129, 35
	v_readlane_b32 s41, v129, 36
	v_readlane_b32 s42, v129, 37
	v_readlane_b32 s43, v129, 38
	v_readlane_b32 s45, v129, 39
	v_readlane_b32 s46, v129, 40
	v_readlane_b32 s47, v129, 41
	v_readlane_b32 s49, v129, 42
	v_readlane_b32 s57, v129, 43
	v_readlane_b32 s58, v129, 44
	v_readlane_b32 s59, v129, 45
	v_readlane_b32 s72, v129, 46
	v_readlane_b32 s73, v129, 47
	v_readlane_b32 s76, v129, 48
	v_readlane_b32 s77, v129, 49
	v_readlane_b32 s78, v129, 50
	v_readlane_b32 s79, v129, 51
	v_readlane_b32 s80, v129, 52
	v_readlane_b32 s81, v129, 53
	v_readlane_b32 s84, v129, 54
	v_readlane_b32 s85, v129, 55
	v_readlane_b32 s86, v129, 56
	v_readlane_b32 s87, v129, 57
	v_readlane_b32 s88, v129, 58
	v_readlane_b32 s89, v129, 59
	v_readlane_b32 s90, v129, 60
	v_readlane_b32 s91, v129, 61
	v_readlane_b32 s92, v129, 62
	v_readlane_b32 s93, v129, 63
	s_cmp_lt_i32 s61, 20
	s_cbranch_scc1 .LBB0_1390
	s_waitcnt vmcnt(0)
	v_cmp_eq_u32_e32 vcc, 0, v0
	s_barrier
	s_and_saveexec_b64 s[4:5], vcc
	s_cbranch_execz .LBB0_1389
	v_readlane_b32 s3, v255, 10
	s_waitcnt vmcnt(0) expcnt(0) lgkmcnt(0)
	s_nop 0
	v_mov_b32_e32 v1, s3
	ds_read_b32 v3, v1
	ds_read_b32 v1, v1 offset:4
	s_waitcnt lgkmcnt(1)
	v_cmp_ne_u32_e32 vcc, 0, v3
	s_cbranch_vccnz .LBB0_1357
	v_readlane_b32 s6, v255, 0
	v_readlane_b32 s7, v255, 1
	s_load_dwordx2 s[10:11], s[6:7], 0x4
	s_add_u32 s6, s52, 0x4200
	s_addc_u32 s7, s53, 0
	s_add_u32 s8, s52, 0x4400
	s_addc_u32 s9, s53, 0
	s_waitcnt lgkmcnt(0)
	s_mul_i32 s3, s10, s56
	s_add_u32 s10, s52, 0x4500
	s_mul_i32 s3, s3, s11
	s_addc_u32 s11, s53, 0
	s_add_u32 s12, s52, 0x4600
	s_addc_u32 s13, s53, 0
	s_add_u32 s14, s52, 0x4700
	s_addc_u32 s15, s53, 0
	s_add_u32 s16, s52, 0x4800
	s_addc_u32 s17, s53, 0
	s_add_u32 s18, s52, 0x4900
	s_addc_u32 s19, s53, 0
	s_add_u32 s20, s52, 0x4a00
	s_addc_u32 s21, s53, 0
	s_add_u32 s22, s52, 0x4b00
	s_addc_u32 s23, s53, 0
	s_add_u32 s24, s52, 0x4c00
	s_addc_u32 s25, s53, 0
	s_add_u32 s26, s52, 0x4d00
	s_addc_u32 s27, s53, 0
	s_add_u32 s28, s52, 0x4e00
	s_addc_u32 s29, s53, 0
	s_add_u32 s30, s52, 0x4f00
	s_addc_u32 s31, s53, 0
	s_add_u32 s34, s52, 0x5000
	s_addc_u32 s35, s53, 0
	s_add_u32 s36, s52, 0x5100
	s_addc_u32 s37, s53, 0
	s_add_u32 s38, s52, 0x5200
	s_addc_u32 s39, s53, 0
	s_add_u32 s42, s52, 0x5300
	s_addc_u32 s43, s53, 0
	s_mov_b32 s41, 1
	v_mov_b32_e32 v17, 0
	s_branch .LBB0_1345

.LBB0_1885:
	s_cmp_lt_i32 s61, 27
	s_cbranch_scc1 .LBB0_2670
	s_cmp_gt_i32 s60, 26
	s_cbranch_scc1 .LBB0_1959
	s_cmpk_lg_i32 s56, 0x100
	s_cselect_b64 s[4:5], -1, 0
	s_cmp_lt_i32 s2, 48
	s_cselect_b64 s[6:7], -1, 0
	s_or_b64 s[4:5], s[6:7], s[4:5]
	s_and_b64 vcc, exec, s[4:5]
	s_cbranch_vccnz .LBB0_1895
	s_add_i32 s3, s54, 0xca80
	s_cmp_gt_i32 s3, 0
	s_cbranch_scc1 .LBB0_1895
	v_readlane_b32 s4, v255, 6
	s_mulk_i32 s4, 0x2200
	s_add_i32 s11, s4, 0
	v_and_b32_e32 v1, 63, v0
	s_mov_b32 s5, 0
	s_mov_b32 s10, 0x10000
	s_add_i32 s11, s11, 0x10000
	s_lshl_b32 s12, s3, 1
	s_lshl_b32 s13, s3, 5
	s_waitcnt vmcnt(0)
	v_mov_b32_e32 v3, 0
	s_movk_i32 s14, 0x2000
	s_movk_i32 s15, 0x4000
	s_movk_i32 s16, 0x6000
	s_mov_b32 s17, 0x8000
	s_mov_b32 s18, 0xa000
	s_mov_b32 s19, 0xc000
	s_mov_b32 s20, 0xe000
	s_mov_b32 s21, 0x12000
	s_mov_b32 s22, 0x14000
	s_mov_b32 s23, 0x16000
	s_mov_b32 s24, 0x18000
	s_mov_b32 s25, 0x1a000
	s_mov_b32 s26, 0x1c000
	s_mov_b32 s27, 0x1e000
	s_mov_b32 s28, 0x20000
	s_mov_b32 s29, 0x22000
	s_mov_b32 s30, 0x24000
	s_mov_b32 s31, 0x26000
	s_mov_b32 s34, 0x28000
	s_mov_b32 s35, 0x2a000
	s_mov_b32 s36, 0x2c000
	s_mov_b32 s37, 0x2e000
	s_mov_b32 s38, 0x30000
	s_mov_b32 s39, 0x32000
	s_mov_b32 s41, 0x34000
	s_mov_b32 s42, 0x36000
	s_mov_b32 s43, 0x38000
	s_mov_b32 s45, 0x3a000
	s_mov_b32 s46, 0x3c000
	s_mov_b32 s47, 0x3e000
	s_movk_i32 s49, 0x84
	s_movk_i32 s50, 0xc8
	s_branch .LBB0_1891

.LBB0_1909:
	v_writelane_b32 v129, s3, 0
	v_writelane_b32 v129, s4, 1
	v_writelane_b32 v129, s5, 2
	v_writelane_b32 v129, s6, 3
	v_writelane_b32 v129, s7, 4
	v_writelane_b32 v129, s8, 5
	v_writelane_b32 v129, s9, 6
	v_writelane_b32 v129, s10, 7
	v_writelane_b32 v129, s11, 8
	v_writelane_b32 v129, s12, 9
	v_writelane_b32 v129, s13, 10
	v_writelane_b32 v129, s14, 11
	v_writelane_b32 v129, s15, 12
	v_writelane_b32 v129, s16, 13
	v_writelane_b32 v129, s17, 14
	v_writelane_b32 v129, s18, 15
	v_writelane_b32 v129, s19, 16
	v_writelane_b32 v129, s20, 17
	v_writelane_b32 v129, s21, 18
	v_writelane_b32 v129, s22, 19
	v_writelane_b32 v129, s23, 20
	v_writelane_b32 v129, s24, 21
	v_writelane_b32 v129, s25, 22
	v_writelane_b32 v129, s26, 23
	v_writelane_b32 v129, s27, 24
	v_writelane_b32 v129, s28, 25
	v_writelane_b32 v129, s29, 26
	v_writelane_b32 v129, s30, 27
	v_writelane_b32 v129, s31, 28
	v_writelane_b32 v129, s33, 29
	v_writelane_b32 v129, s34, 30
	v_writelane_b32 v129, s35, 31
	v_writelane_b32 v129, s36, 32
	v_writelane_b32 v129, s37, 33
	v_writelane_b32 v129, s38, 34
	v_writelane_b32 v129, s39, 35
	v_writelane_b32 v129, s41, 36
	v_writelane_b32 v129, s42, 37
	v_writelane_b32 v129, s43, 38
	v_writelane_b32 v129, s45, 39
	v_writelane_b32 v129, s46, 40
	v_writelane_b32 v129, s47, 41
	v_writelane_b32 v129, s49, 42
	v_writelane_b32 v129, s57, 43
	v_writelane_b32 v129, s58, 44
	v_writelane_b32 v129, s59, 45
	v_writelane_b32 v129, s72, 46
	v_writelane_b32 v129, s73, 47
	v_writelane_b32 v129, s76, 48
	v_writelane_b32 v129, s77, 49
	v_writelane_b32 v129, s78, 50
	v_writelane_b32 v129, s79, 51
	v_writelane_b32 v129, s80, 52
	v_writelane_b32 v129, s81, 53
	v_writelane_b32 v129, s84, 54
	v_writelane_b32 v129, s85, 55
	v_writelane_b32 v129, s86, 56
	v_writelane_b32 v129, s87, 57
	v_writelane_b32 v129, s88, 58
	v_writelane_b32 v129, s89, 59
	v_writelane_b32 v129, s90, 60
	v_writelane_b32 v129, s91, 61
	v_writelane_b32 v129, s92, 62
	v_writelane_b32 v129, s93, 63
	s_cmpk_lt_u32 s2, 0x30
	s_cselect_b64 s[4:5], -1, 0
	s_cmpk_gt_u32 s2, 0x2f
	s_cselect_b64 s[10:11], -1, 0
	s_mov_b32 s3, 0xcc00
	s_and_b64 s[6:7], s[10:11], exec
	s_cselect_b32 s12, s3, 0x10d00
	s_mov_b32 s3, 0x10d00
	s_cselect_b32 s13, 0x10d00, s3
	s_add_i32 s14, s54, 0xc000
	s_cmpk_eq_i32 s56, 0x100
	s_cselect_b64 s[6:7], -1, 0
	s_and_b64 s[8:9], s[6:7], exec
	s_cselect_b32 s18, s13, 0
	s_cselect_b32 s19, s12, s14
	s_mov_b32 s3, 0xc000
	s_cmp_ge_u32 s19, s18
	s_mov_b32 s20, 0x12000
	s_waitcnt vmcnt(0)
	s_barrier
	s_cbranch_scc1 .Lcvl3_end
	v_readlane_b32 s8, v255, 7
	s_sub_i32 s8, s8, 0x180
	v_readlane_b32 s13, v255, 6
	s_add_i32 s21, s13, s8
	s_lshl_b32 s22, s21, 1
	s_movk_i32 s12, 0xd00
	s_and_b64 s[8:9], s[10:11], exec
	s_cselect_b32 s12, s12, 0x400
	s_and_b64 s[8:9], s[6:7], exec
	s_mul_i32 s8, s13, 0x2200
	s_cselect_b32 s23, s12, s55
	s_add_i32 s25, s8, 0
	v_cndmask_b32_e64 v2, 0, 1, s[4:5]
	v_and_b32_e32 v1, 63, v0
	s_mov_b32 s9, 0
	s_mov_b32 s24, 0x10000
	s_add_i32 s25, s25, 0x10000
	s_and_b64 s[10:11], s[10:11], s[6:7]
	v_cmp_ne_u32_e64 s[4:5], 1, v2
	v_mov_b32_e32 v3, 0
	s_movk_i32 s26, 0x2000
	s_movk_i32 s27, 0x4000
	s_movk_i32 s28, 0x6000
	s_mov_b32 s29, 0x8000
	s_mov_b32 s30, 0xa000
	s_mov_b32 s31, 0xe000
	s_mov_b32 s34, 0x14000
	s_mov_b32 s35, 0x16000
	s_mov_b32 s36, 0x18000
	s_mov_b32 s37, 0x1a000
	s_mov_b32 s38, 0x1c000
	s_mov_b32 s39, 0x1e000
	s_mov_b32 s41, 0x20000
	s_mov_b32 s42, 0x22000
	s_mov_b32 s43, 0x24000
	s_mov_b32 s45, 0x26000
	s_mov_b32 s46, 0x28000
	s_mov_b32 s47, 0x2a000
	s_mov_b32 s49, 0x2c000
	s_mov_b32 s57, 0x2e000
	s_mov_b32 s58, 0x30000
	s_mov_b32 s59, 0x32000
	s_mov_b32 s72, 0x34000
	s_mov_b32 s73, 0x36000
	s_mov_b32 s78, 0x38000
	s_mov_b32 s79, 0x3a000
	s_mov_b32 s84, 0x3c000
	s_mov_b32 s85, 0x3e000
	s_movk_i32 s86, 0x84
	s_branch .Lcvl3_2352

.Lcvl3_end:
	s_waitcnt vmcnt(0) lgkmcnt(0)
	s_barrier
	v_readlane_b32 s3, v129, 0
	v_readlane_b32 s4, v129, 1
	v_readlane_b32 s5, v129, 2
	v_readlane_b32 s6, v129, 3
	v_readlane_b32 s7, v129, 4
	v_readlane_b32 s8, v129, 5
	v_readlane_b32 s9, v129, 6
	v_readlane_b32 s10, v129, 7
	v_readlane_b32 s11, v129, 8
	v_readlane_b32 s12, v129, 9
	v_readlane_b32 s13, v129, 10
	v_readlane_b32 s14, v129, 11
	v_readlane_b32 s15, v129, 12
	v_readlane_b32 s16, v129, 13
	v_readlane_b32 s17, v129, 14
	v_readlane_b32 s18, v129, 15
	v_readlane_b32 s19, v129, 16
	v_readlane_b32 s20, v129, 17
	v_readlane_b32 s21, v129, 18
	v_readlane_b32 s22, v129, 19
	v_readlane_b32 s23, v129, 20
	v_readlane_b32 s24, v129, 21
	v_readlane_b32 s25, v129, 22
	v_readlane_b32 s26, v129, 23
	v_readlane_b32 s27, v129, 24
	v_readlane_b32 s28, v129, 25
	v_readlane_b32 s29, v129, 26
	v_readlane_b32 s30, v129, 27
	v_readlane_b32 s31, v129, 28
	v_readlane_b32 s33, v129, 29
	v_readlane_b32 s34, v129, 30
	v_readlane_b32 s35, v129, 31
	v_readlane_b32 s36, v129, 32
	v_readlane_b32 s37, v129, 33
	v_readlane_b32 s38, v129, 34
	v_readlane_b32 s39, v129, 35
	v_readlane_b32 s41, v129, 36
	v_readlane_b32 s42, v129, 37
	v_readlane_b32 s43, v129, 38
	v_readlane_b32 s45, v129, 39
	v_readlane_b32 s46, v129, 40
	v_readlane_b32 s47, v129, 41
	v_readlane_b32 s49, v129, 42
	v_readlane_b32 s57, v129, 43
	v_readlane_b32 s58, v129, 44
	v_readlane_b32 s59, v129, 45
	v_readlane_b32 s72, v129, 46
	v_readlane_b32 s73, v129, 47
	v_readlane_b32 s76, v129, 48
	v_readlane_b32 s77, v129, 49
	v_readlane_b32 s78, v129, 50
	v_readlane_b32 s79, v129, 51
	v_readlane_b32 s80, v129, 52
	v_readlane_b32 s81, v129, 53
	v_readlane_b32 s84, v129, 54
	v_readlane_b32 s85, v129, 55
	v_readlane_b32 s86, v129, 56
	v_readlane_b32 s87, v129, 57
	v_readlane_b32 s88, v129, 58
	v_readlane_b32 s89, v129, 59
	v_readlane_b32 s90, v129, 60
	v_readlane_b32 s91, v129, 61
	v_readlane_b32 s92, v129, 62
	v_readlane_b32 s93, v129, 63
	s_cmp_eq_u32 s61, 27
	s_cbranch_scc1 .LBB0_1959
	s_waitcnt vmcnt(0)
	v_cmp_eq_u32_e32 vcc, 0, v0
	s_waitcnt vmcnt(16)
	s_barrier
	s_and_saveexec_b64 s[4:5], vcc
	s_cbranch_execz .LBB0_1958
	v_readlane_b32 s3, v255, 10
	s_waitcnt vmcnt(0) expcnt(0) lgkmcnt(0)
	s_nop 0
	v_mov_b32_e32 v1, s3
	ds_read_b32 v3, v1
	ds_read_b32 v1, v1 offset:4
	s_waitcnt lgkmcnt(1)
	v_cmp_ne_u32_e32 vcc, 0, v3
	s_cbranch_vccnz .LBB0_1926
	v_readlane_b32 s6, v255, 0
	v_readlane_b32 s7, v255, 1
	s_load_dwordx2 s[10:11], s[6:7], 0x4
	s_add_u32 s6, s52, 0x4200
	s_addc_u32 s7, s53, 0
	s_add_u32 s8, s52, 0x4400
	s_addc_u32 s9, s53, 0
	s_waitcnt lgkmcnt(0)
	s_mul_i32 s3, s10, s56
	s_add_u32 s10, s52, 0x4500
	s_mul_i32 s3, s3, s11
	s_addc_u32 s11, s53, 0
	s_add_u32 s12, s52, 0x4600
	s_addc_u32 s13, s53, 0
	s_add_u32 s14, s52, 0x4700
	s_addc_u32 s15, s53, 0
	s_add_u32 s16, s52, 0x4800
	s_addc_u32 s17, s53, 0
	s_add_u32 s18, s52, 0x4900
	s_addc_u32 s19, s53, 0
	s_add_u32 s20, s52, 0x4a00
	s_addc_u32 s21, s53, 0
	s_add_u32 s22, s52, 0x4b00
	s_addc_u32 s23, s53, 0
	s_add_u32 s24, s52, 0x4c00
	s_addc_u32 s25, s53, 0
	s_add_u32 s26, s52, 0x4d00
	s_addc_u32 s27, s53, 0
	s_add_u32 s28, s52, 0x4e00
	s_addc_u32 s29, s53, 0
	s_add_u32 s30, s52, 0x4f00
	s_addc_u32 s31, s53, 0
	s_add_u32 s34, s52, 0x5000
	s_addc_u32 s35, s53, 0
	s_add_u32 s36, s52, 0x5100
	s_addc_u32 s37, s53, 0
	s_add_u32 s38, s52, 0x5200
	s_addc_u32 s39, s53, 0
	s_add_u32 s42, s52, 0x5300
	s_addc_u32 s43, s53, 0
	s_mov_b32 s41, 1
	v_mov_b32_e32 v17, 0
	s_branch .LBB0_1914
